# same as the 104/88-streamer version plus two idle slots between packed-f32 results and their first scalar-f32 or store consumer in the decode loop (defensive spacing)
# speedup vs baseline: 1.0370x; 1.0027x over previous
; __device__ __forceinline__ void sb_decode_stream(Frame& F, unsigned* qctr, int base, int limit) {
;     ...
;         DEC_SCORES(A, 0);
; #pragma unroll
;         for (int i = 0; i < 16; ++i) A[i] = __builtin_nontemporal_load((const f32x4*)(CV + cb + (size_t)(2 * i) * (NH * HD)));
;         DEC_SCORES(B, 1);
;     ...
; #pragma unroll
;         for (int i = 0; i < 16; ++i) B[i] = __builtin_nontemporal_load((const f32x4*)(CV + cb + (size_t)(32 + 2 * i) * (NH * HD)));
;         const float z = __builtin_bit_cast(float, zi);
;         const float e = __builtin_amdgcn_exp2f(-(z * k1 + k2));
;         const float be = __builtin_amdgcn_rcpf(1.0f + e), m = 1.0f - be;
;         float s = m;
; #pragma unroll
;         for (int o = 1; o < 64; o <<= 1) { const float t = __shfl_down(s, o); if (lane + o < 64) s *= t; }
;         const float tot = __shfl(s, 0);
;         const float sx = __shfl_down(s, 1);
;         const float a = be * (lane < 63 ? sx : 1.0f);
;         int itn = (int)(__builtin_amdgcn_readfirstlane(vn) >> 6); const bool more = itn < limit; itn = more ? itn + base : it;
;         const int bn = itn >> 11, hn = itn & 7, p0n = ((itn >> 3) & 255) * 64;
;         const int pagen = PT[bn * NPAGES + (p0n >> 7)];
;         const size_t cbn = (((size_t)pagen * PAGE + (p0n & 127)) * NH + hn) * HD + lo;
;         const size_t stepn = more ? (size_t)(NH * HD) : 0;
;         f32x4 o4 = {0.f, 0.f, 0.f, 0.f};
; #pragma unroll
;         for (int i = 0; i < 16; ++i) { const float aj = __shfl(a, 2 * i + half); o4 += aj * A[i]; }
;         const f32x4 q4n = *(const f32x4*)(SSP(S_PROJ) + (size_t)bn * IN_COLS + hn * HD + 4 * l32);
; #pragma unroll
;         for (int i = 0; i < 16; ++i) A[i] = __builtin_nontemporal_load((const f32x4*)(CK + cbn + (size_t)(2 * i) * stepn));
.Ldqa_sh2:
	s_barrier
	ds_read_b32 v201, v200
	s_xor_b32 s37, s37, 4
	s_waitcnt lgkmcnt(0)
	v_readfirstlane_b32 s2, v201
	s_nop 0
	s_lshr_b32 s73, s2, 6
	s_cmp_lt_u32 s73, 0x1800
	s_cselect_b32 s31, 1, 0
	s_add_u32 s73, s73, s94
	s_min_u32 s73, s73, 0x17ff
	s_cmp_eq_u32 s31, 1
	s_cselect_b32 s73, s73, s72
	s_lshr_b32 s6, s73, 11
	s_and_b32 s7, s73, 7
	s_bfe_u32 s8, s73, 0x80003
	s_lshl_b32 s9, s6, 7
	s_lshr_b32 s10, s8, 1
	s_or_b32 s9, s9, s10
	s_lshl_b32 s9, s9, 2
	s_lshl_b32 s10, s7, 2
	s_load_dword s29, s[54:55], s9
	s_load_dword s30, s[56:57], s10
	v_add_f32_dpp v132, v132, v132 row_ror:8 row_mask:0xf bank_mask:0x3
	v_add_f32_dpp v133, v133, v133 row_ror:8 row_mask:0xf bank_mask:0x3
	v_add_f32_dpp v134, v134, v134 row_ror:8 row_mask:0xf bank_mask:0x3
	v_add_f32_dpp v135, v135, v135 row_ror:8 row_mask:0xf bank_mask:0x3
	v_add_f32_dpp v136, v136, v136 row_ror:8 row_mask:0xf bank_mask:0x3
	v_add_f32_dpp v137, v137, v137 row_ror:8 row_mask:0xf bank_mask:0x3
	v_add_f32_dpp v138, v138, v138 row_ror:8 row_mask:0xf bank_mask:0x3
	v_add_f32_dpp v139, v139, v139 row_ror:8 row_mask:0xf bank_mask:0x3
	v_add_f32_dpp v132, v140, v140 row_ror:8 row_mask:0xf bank_mask:0xc
	v_add_f32_dpp v133, v141, v141 row_ror:8 row_mask:0xf bank_mask:0xc
	v_add_f32_dpp v134, v142, v142 row_ror:8 row_mask:0xf bank_mask:0xc
	v_add_f32_dpp v135, v143, v143 row_ror:8 row_mask:0xf bank_mask:0xc
	v_add_f32_dpp v136, v144, v144 row_ror:8 row_mask:0xf bank_mask:0xc
	v_add_f32_dpp v137, v145, v145 row_ror:8 row_mask:0xf bank_mask:0xc
	v_add_f32_dpp v138, v146, v146 row_ror:8 row_mask:0xf bank_mask:0xc
	v_add_f32_dpp v139, v147, v147 row_ror:8 row_mask:0xf bank_mask:0xc
	v_add_f32_dpp v132, v132, v132 row_ror:12 row_mask:0xf bank_mask:0x5
	v_add_f32_dpp v133, v133, v133 row_ror:12 row_mask:0xf bank_mask:0x5
	v_add_f32_dpp v134, v134, v134 row_ror:12 row_mask:0xf bank_mask:0x5
	v_add_f32_dpp v135, v135, v135 row_ror:12 row_mask:0xf bank_mask:0x5
	v_add_f32_dpp v132, v136, v136 row_ror:4 row_mask:0xf bank_mask:0xa
	v_add_f32_dpp v133, v137, v137 row_ror:4 row_mask:0xf bank_mask:0xa
	v_add_f32_dpp v134, v138, v138 row_ror:4 row_mask:0xf bank_mask:0xa
	v_add_f32_dpp v135, v139, v139 row_ror:4 row_mask:0xf bank_mask:0xa
	v_add_f32_dpp v140, v132, v132 quad_perm:[2,3,0,1] row_mask:0xf bank_mask:0xf
	v_add_f32_dpp v142, v134, v134 quad_perm:[2,3,0,1] row_mask:0xf bank_mask:0xf
	v_add_f32_dpp v141, v133, v133 quad_perm:[2,3,0,1] row_mask:0xf bank_mask:0xf
	v_add_f32_dpp v143, v135, v135 quad_perm:[2,3,0,1] row_mask:0xf bank_mask:0xf
	v_cndmask_b32_e64 v132, v140, v142, s[76:77]
	v_cndmask_b32_e64 v133, v141, v143, s[76:77]
	s_nop 0
	v_add_f32_dpp v196, v132, v132 quad_perm:[1,0,3,2] row_mask:0xf bank_mask:0xf
	v_add_f32_dpp v197, v133, v133 quad_perm:[1,0,3,2] row_mask:0xf bank_mask:0xf
	v_cndmask_b32_e64 v177, v196, v197, s[78:79]
	s_nop 1
	v_permlane16_swap_b32_e32 v176, v177
	v_add_f32_e32 v178, v176, v177
	v_mul_f32_e32 v178, 0x3e0293ee, v178
	v_add_f32_e32 v178, v178, v192
	v_exp_f32_e64 v198, -v178
	s_nop 0
	v_add_f32_e32 v198, 1.0, v198
	v_rcp_f32_e32 v179, v198
	s_nop 0
	v_sub_f32_e32 v180, 1.0, v179
	v_mov_b32_e32 v181, v180
	s_nop 1
	v_permlane32_swap_b32_e32 v180, v181
	v_mul_f32_e32 v183, v180, v181
	s_nop 1
	v_mul_f32_dpp v183, v183, v183 row_shl:1 row_mask:0xf bank_mask:0xf
	s_nop 1
	v_mul_f32_dpp v183, v183, v183 row_shl:2 row_mask:0xf bank_mask:0xf
	s_nop 1
	v_mul_f32_dpp v183, v183, v183 row_shl:4 row_mask:0xf bank_mask:0xf
	s_nop 1
	v_mul_f32_dpp v183, v183, v183 row_shl:8 row_mask:0xf bank_mask:0xf
	s_nop 0
	v_readlane_b32 s33, v183, 16
	v_mov_b32_e32 v184, 1.0
	s_nop 0
	v_mov_b32_e32 v185, s33
	s_nop 1
	v_mul_f32_dpp v183, v183, v185 quad_perm:[0,1,2,3] row_mask:0x5 bank_mask:0xf
	v_mov_b32_dpp v184, v185 quad_perm:[0,1,2,3] row_mask:0x5 bank_mask:0xf
	s_nop 1
	v_mov_b32_dpp v184, v183 row_shl:1 row_mask:0xf bank_mask:0xf
	v_mul_f32_e32 v186, v179, v184
	s_nop 1
	v_mul_f32_dpp v186, v186, v181 quad_perm:[0,1,2,3] row_mask:0x3 bank_mask:0xf
	s_cmp_eq_u32 s31, 0
	s_cbranch_scc1 .Ldqa_tail
	s_waitcnt lgkmcnt(0)
	s_mov_b32 s12, s29
	s_mov_b32 s13, 0
	s_lshl_b64 s[12:13], s[12:13], 19
	s_and_b32 s14, s8, 1
	s_lshl_b32 s14, s14, 18
	s_lshl_b32 s15, s7, 9
	s_or_b32 s14, s14, s15
	s_or_b32 s80, s12, s14
	s_mov_b32 s81, s13
	s_add_u32 s64, s50, s80
	s_addc_u32 s65, s51, s81
	s_mul_i32 s16, s6, 0x7040
	s_add_u32 s16, s16, s15
	s_add_u32 s16, s60, s16
	s_addc_u32 s17, s61, 0
	global_load_dwordx4 v[156:159], v193, s[16:17]
	v_mov_b32_e32 v160, 0
	v_mov_b32_e32 v161, 0
	v_mov_b32_e32 v162, 0
	v_mov_b32_e32 v163, 0
	v_mov_b32_e32 v164, 0
	v_mov_b32_e32 v165, 0
	v_mov_b32_e32 v166, 0
	v_mov_b32_e32 v167, 0
	ds_bpermute_b32 v168, v188, v186 offset:0
	ds_bpermute_b32 v170, v188, v186 offset:4
	ds_bpermute_b32 v172, v188, v186 offset:8
	ds_bpermute_b32 v174, v188, v186 offset:12
	s_waitcnt vmcnt(32) lgkmcnt(3)
	v_pk_fma_f32 v[160:161], v[4:5], v[168:169], v[160:161] op_sel_hi:[1,0,1]
	v_pk_fma_f32 v[162:163], v[6:7], v[168:169], v[162:163] op_sel_hi:[1,0,1]
	global_load_dwordx4 v[4:7], v187, s[64:65] nt
	s_add_u32 s64, s64, 0x2000
	s_addc_u32 s65, s65, 0
	ds_bpermute_b32 v168, v188, v186 offset:16
	s_waitcnt vmcnt(32) lgkmcnt(3)
	v_pk_fma_f32 v[164:165], v[8:9], v[170:171], v[164:165] op_sel_hi:[1,0,1]
	v_pk_fma_f32 v[166:167], v[10:11], v[170:171], v[166:167] op_sel_hi:[1,0,1]
	global_load_dwordx4 v[8:11], v187, s[64:65] nt
	s_add_u32 s64, s64, 0x2000
	s_addc_u32 s65, s65, 0
	ds_bpermute_b32 v170, v188, v186 offset:20
	s_waitcnt vmcnt(32) lgkmcnt(3)
; __device__ __forceinline__ void sb_decode_stream(Frame& F, unsigned* qctr, int base, int limit) {
;     ...
;         for (int i = 0; i < 16; ++i) { const float aj = __shfl(a, 2 * i + half); o4 += aj * A[i]; }
;         const f32x4 q4n = *(const f32x4*)(SSP(S_PROJ) + (size_t)bn * IN_COLS + hn * HD + 4 * l32);
; #pragma unroll
;         for (int i = 0; i < 16; ++i) A[i] = __builtin_nontemporal_load((const f32x4*)(CK + cbn + (size_t)(2 * i) * stepn));
	v_pk_fma_f32 v[160:161], v[12:13], v[172:173], v[160:161] op_sel_hi:[1,0,1]
	v_pk_fma_f32 v[162:163], v[14:15], v[172:173], v[162:163] op_sel_hi:[1,0,1]
	global_load_dwordx4 v[12:15], v187, s[64:65] nt
	s_add_u32 s64, s64, 0x2000
	s_addc_u32 s65, s65, 0
	ds_bpermute_b32 v172, v188, v186 offset:24
	s_waitcnt vmcnt(32) lgkmcnt(3)
	v_pk_fma_f32 v[164:165], v[16:17], v[174:175], v[164:165] op_sel_hi:[1,0,1]
	v_pk_fma_f32 v[166:167], v[18:19], v[174:175], v[166:167] op_sel_hi:[1,0,1]
	global_load_dwordx4 v[16:19], v187, s[64:65] nt
	s_add_u32 s64, s64, 0x2000
	s_addc_u32 s65, s65, 0
	ds_bpermute_b32 v174, v188, v186 offset:28
	s_waitcnt vmcnt(32) lgkmcnt(3)
	v_pk_fma_f32 v[160:161], v[20:21], v[168:169], v[160:161] op_sel_hi:[1,0,1]
	v_pk_fma_f32 v[162:163], v[22:23], v[168:169], v[162:163] op_sel_hi:[1,0,1]
	global_load_dwordx4 v[20:23], v187, s[64:65] nt
	s_add_u32 s64, s64, 0x2000
	s_addc_u32 s65, s65, 0
	ds_bpermute_b32 v168, v188, v186 offset:32
	s_waitcnt vmcnt(32) lgkmcnt(3)
	v_pk_fma_f32 v[164:165], v[24:25], v[170:171], v[164:165] op_sel_hi:[1,0,1]
	v_pk_fma_f32 v[166:167], v[26:27], v[170:171], v[166:167] op_sel_hi:[1,0,1]
	global_load_dwordx4 v[24:27], v187, s[64:65] nt
	s_add_u32 s64, s64, 0x2000
	s_addc_u32 s65, s65, 0
	ds_bpermute_b32 v170, v188, v186 offset:36
	s_waitcnt vmcnt(32) lgkmcnt(3)
	v_pk_fma_f32 v[160:161], v[28:29], v[172:173], v[160:161] op_sel_hi:[1,0,1]
	v_pk_fma_f32 v[162:163], v[30:31], v[172:173], v[162:163] op_sel_hi:[1,0,1]
	global_load_dwordx4 v[28:31], v187, s[64:65] nt
	s_add_u32 s64, s64, 0x2000
	s_addc_u32 s65, s65, 0
	ds_bpermute_b32 v172, v188, v186 offset:40
	s_waitcnt vmcnt(32) lgkmcnt(3)
	v_pk_fma_f32 v[164:165], v[32:33], v[174:175], v[164:165] op_sel_hi:[1,0,1]
	v_pk_fma_f32 v[166:167], v[34:35], v[174:175], v[166:167] op_sel_hi:[1,0,1]
	global_load_dwordx4 v[32:35], v187, s[64:65] nt
	s_add_u32 s64, s64, 0x2000
	s_addc_u32 s65, s65, 0
	ds_bpermute_b32 v174, v188, v186 offset:44
	s_waitcnt vmcnt(32) lgkmcnt(3)
	v_pk_fma_f32 v[160:161], v[36:37], v[168:169], v[160:161] op_sel_hi:[1,0,1]
	v_pk_fma_f32 v[162:163], v[38:39], v[168:169], v[162:163] op_sel_hi:[1,0,1]
	global_load_dwordx4 v[36:39], v187, s[64:65] nt
	s_add_u32 s64, s64, 0x2000
	s_addc_u32 s65, s65, 0
	ds_bpermute_b32 v168, v188, v186 offset:48
	s_waitcnt vmcnt(32) lgkmcnt(3)
	v_pk_fma_f32 v[164:165], v[40:41], v[170:171], v[164:165] op_sel_hi:[1,0,1]
	v_pk_fma_f32 v[166:167], v[42:43], v[170:171], v[166:167] op_sel_hi:[1,0,1]
	global_load_dwordx4 v[40:43], v187, s[64:65] nt
	s_add_u32 s64, s64, 0x2000
	s_addc_u32 s65, s65, 0
	ds_bpermute_b32 v170, v188, v186 offset:52
	s_waitcnt vmcnt(32) lgkmcnt(3)
	v_pk_fma_f32 v[160:161], v[44:45], v[172:173], v[160:161] op_sel_hi:[1,0,1]
	v_pk_fma_f32 v[162:163], v[46:47], v[172:173], v[162:163] op_sel_hi:[1,0,1]
	global_load_dwordx4 v[44:47], v187, s[64:65] nt
	s_add_u32 s64, s64, 0x2000
	s_addc_u32 s65, s65, 0
	ds_bpermute_b32 v172, v188, v186 offset:56
	s_waitcnt vmcnt(32) lgkmcnt(3)
	v_pk_fma_f32 v[164:165], v[48:49], v[174:175], v[164:165] op_sel_hi:[1,0,1]
	v_pk_fma_f32 v[166:167], v[50:51], v[174:175], v[166:167] op_sel_hi:[1,0,1]
	global_load_dwordx4 v[48:51], v187, s[64:65] nt
	s_add_u32 s64, s64, 0x2000
	s_addc_u32 s65, s65, 0
	ds_bpermute_b32 v174, v188, v186 offset:60
	s_waitcnt vmcnt(32) lgkmcnt(3)
	v_pk_fma_f32 v[160:161], v[52:53], v[168:169], v[160:161] op_sel_hi:[1,0,1]
	v_pk_fma_f32 v[162:163], v[54:55], v[168:169], v[162:163] op_sel_hi:[1,0,1]
	global_load_dwordx4 v[52:55], v187, s[64:65] nt
	s_add_u32 s64, s64, 0x2000
	s_addc_u32 s65, s65, 0
	ds_bpermute_b32 v168, v188, v186 offset:64
	s_waitcnt vmcnt(32) lgkmcnt(3)
	v_pk_fma_f32 v[164:165], v[56:57], v[170:171], v[164:165] op_sel_hi:[1,0,1]
	v_pk_fma_f32 v[166:167], v[58:59], v[170:171], v[166:167] op_sel_hi:[1,0,1]
	global_load_dwordx4 v[56:59], v187, s[64:65] nt
	s_add_u32 s64, s64, 0x2000
	s_addc_u32 s65, s65, 0
	ds_bpermute_b32 v170, v188, v186 offset:68
	s_waitcnt vmcnt(32) lgkmcnt(3)
	v_pk_fma_f32 v[160:161], v[60:61], v[172:173], v[160:161] op_sel_hi:[1,0,1]
	v_pk_fma_f32 v[162:163], v[62:63], v[172:173], v[162:163] op_sel_hi:[1,0,1]
	global_load_dwordx4 v[60:63], v187, s[64:65] nt
	s_add_u32 s64, s64, 0x2000
	s_addc_u32 s65, s65, 0
	ds_bpermute_b32 v172, v188, v186 offset:72
	s_waitcnt vmcnt(32) lgkmcnt(3)
	v_pk_fma_f32 v[164:165], v[64:65], v[174:175], v[164:165] op_sel_hi:[1,0,1]
	v_pk_fma_f32 v[166:167], v[66:67], v[174:175], v[166:167] op_sel_hi:[1,0,1]
	global_load_dwordx4 v[64:67], v187, s[64:65] nt
	s_add_u32 s64, s64, 0x2000
	s_addc_u32 s65, s65, 0
	ds_bpermute_b32 v174, v188, v186 offset:76
	s_waitcnt vmcnt(32) lgkmcnt(3)
	v_pk_fma_f32 v[160:161], v[68:69], v[168:169], v[160:161] op_sel_hi:[1,0,1]
	v_pk_fma_f32 v[162:163], v[70:71], v[168:169], v[162:163] op_sel_hi:[1,0,1]
	global_load_dwordx4 v[68:71], v187, s[64:65] nt
	s_add_u32 s64, s64, 0x2000
	s_addc_u32 s65, s65, 0
	ds_bpermute_b32 v168, v188, v186 offset:80
	s_waitcnt vmcnt(32) lgkmcnt(3)
	v_pk_fma_f32 v[164:165], v[72:73], v[170:171], v[164:165] op_sel_hi:[1,0,1]
	v_pk_fma_f32 v[166:167], v[74:75], v[170:171], v[166:167] op_sel_hi:[1,0,1]
	global_load_dwordx4 v[72:75], v187, s[64:65] nt
	s_add_u32 s64, s64, 0x2000
	s_addc_u32 s65, s65, 0
	ds_bpermute_b32 v170, v188, v186 offset:84
	s_waitcnt vmcnt(32) lgkmcnt(3)
	v_pk_fma_f32 v[160:161], v[76:77], v[172:173], v[160:161] op_sel_hi:[1,0,1]
	v_pk_fma_f32 v[162:163], v[78:79], v[172:173], v[162:163] op_sel_hi:[1,0,1]
	global_load_dwordx4 v[76:79], v187, s[64:65] nt
	s_add_u32 s64, s64, 0x2000
	s_addc_u32 s65, s65, 0
	ds_bpermute_b32 v172, v188, v186 offset:88
	s_waitcnt vmcnt(32) lgkmcnt(3)
; __device__ __forceinline__ void sb_decode_stream(Frame& F, unsigned* qctr, int base, int limit) {
;     ...
;         for (int i = 0; i < 16; ++i) { const float aj = __shfl(a, 2 * i + half); o4 += aj * A[i]; }
;         const f32x4 q4n = *(const f32x4*)(SSP(S_PROJ) + (size_t)bn * IN_COLS + hn * HD + 4 * l32);
; #pragma unroll
;         for (int i = 0; i < 16; ++i) A[i] = __builtin_nontemporal_load((const f32x4*)(CK + cbn + (size_t)(2 * i) * stepn));
; #pragma unroll
;         for (int i = 0; i < 16; ++i) { const float aj = __shfl(a, 32 + 2 * i + half); o4 += aj * B[i]; }
; #pragma unroll
;         for (int i = 0; i < 16; ++i) B[i] = __builtin_nontemporal_load((const f32x4*)(CK + cbn + (size_t)(32 + 2 * i) * stepn));
;         o4.x += __shfl_xor(o4.x, 32); o4.y += __shfl_xor(o4.y, 32); o4.z += __shfl_xor(o4.z, 32); o4.w += __shfl_xor(o4.w, 32);
;         float* P = SSP(S_PART) + ((size_t)bh * DSEG + blk) * DPART;
;         if (half == 0) *(f32x4*)(P + 4 * l32) = o4; if (lane == 0) P[128] = tot;
;         if (!more) break;
;         it = itn; cb = cbn; q4 = q4n;
;     }
	v_pk_fma_f32 v[164:165], v[80:81], v[174:175], v[164:165] op_sel_hi:[1,0,1]
	v_pk_fma_f32 v[166:167], v[82:83], v[174:175], v[166:167] op_sel_hi:[1,0,1]
	global_load_dwordx4 v[80:83], v187, s[64:65] nt
	s_add_u32 s64, s64, 0x2000
	s_addc_u32 s65, s65, 0
	ds_bpermute_b32 v174, v188, v186 offset:92
	s_waitcnt vmcnt(32) lgkmcnt(3)
	v_pk_fma_f32 v[160:161], v[84:85], v[168:169], v[160:161] op_sel_hi:[1,0,1]
	v_pk_fma_f32 v[162:163], v[86:87], v[168:169], v[162:163] op_sel_hi:[1,0,1]
	global_load_dwordx4 v[84:87], v187, s[64:65] nt
	s_add_u32 s64, s64, 0x2000
	s_addc_u32 s65, s65, 0
	ds_bpermute_b32 v168, v188, v186 offset:96
	s_waitcnt vmcnt(32) lgkmcnt(3)
	v_pk_fma_f32 v[164:165], v[88:89], v[170:171], v[164:165] op_sel_hi:[1,0,1]
	v_pk_fma_f32 v[166:167], v[90:91], v[170:171], v[166:167] op_sel_hi:[1,0,1]
	global_load_dwordx4 v[88:91], v187, s[64:65] nt
	s_add_u32 s64, s64, 0x2000
	s_addc_u32 s65, s65, 0
	ds_bpermute_b32 v170, v188, v186 offset:100
	s_waitcnt vmcnt(32) lgkmcnt(3)
	v_pk_fma_f32 v[160:161], v[92:93], v[172:173], v[160:161] op_sel_hi:[1,0,1]
	v_pk_fma_f32 v[162:163], v[94:95], v[172:173], v[162:163] op_sel_hi:[1,0,1]
	global_load_dwordx4 v[92:95], v187, s[64:65] nt
	s_add_u32 s64, s64, 0x2000
	s_addc_u32 s65, s65, 0
	ds_bpermute_b32 v172, v188, v186 offset:104
	s_waitcnt vmcnt(32) lgkmcnt(3)
	v_pk_fma_f32 v[164:165], v[96:97], v[174:175], v[164:165] op_sel_hi:[1,0,1]
	v_pk_fma_f32 v[166:167], v[98:99], v[174:175], v[166:167] op_sel_hi:[1,0,1]
	global_load_dwordx4 v[96:99], v187, s[64:65] nt
	s_add_u32 s64, s64, 0x2000
	s_addc_u32 s65, s65, 0
	ds_bpermute_b32 v174, v188, v186 offset:108
	s_waitcnt vmcnt(32) lgkmcnt(3)
	v_pk_fma_f32 v[160:161], v[100:101], v[168:169], v[160:161] op_sel_hi:[1,0,1]
	v_pk_fma_f32 v[162:163], v[102:103], v[168:169], v[162:163] op_sel_hi:[1,0,1]
	global_load_dwordx4 v[100:103], v187, s[64:65] nt
	s_add_u32 s64, s64, 0x2000
	s_addc_u32 s65, s65, 0
	ds_bpermute_b32 v168, v188, v186 offset:112
	s_waitcnt vmcnt(32) lgkmcnt(3)
	v_pk_fma_f32 v[164:165], v[104:105], v[170:171], v[164:165] op_sel_hi:[1,0,1]
	v_pk_fma_f32 v[166:167], v[106:107], v[170:171], v[166:167] op_sel_hi:[1,0,1]
	global_load_dwordx4 v[104:107], v187, s[64:65] nt
	s_add_u32 s64, s64, 0x2000
	s_addc_u32 s65, s65, 0
	ds_bpermute_b32 v170, v188, v186 offset:116
	s_waitcnt vmcnt(32) lgkmcnt(3)
	v_pk_fma_f32 v[160:161], v[108:109], v[172:173], v[160:161] op_sel_hi:[1,0,1]
	v_pk_fma_f32 v[162:163], v[110:111], v[172:173], v[162:163] op_sel_hi:[1,0,1]
	global_load_dwordx4 v[108:111], v187, s[64:65] nt
	s_add_u32 s64, s64, 0x2000
	s_addc_u32 s65, s65, 0
	ds_bpermute_b32 v172, v188, v186 offset:120
	s_waitcnt vmcnt(32) lgkmcnt(3)
	v_pk_fma_f32 v[164:165], v[112:113], v[174:175], v[164:165] op_sel_hi:[1,0,1]
	v_pk_fma_f32 v[166:167], v[114:115], v[174:175], v[166:167] op_sel_hi:[1,0,1]
	global_load_dwordx4 v[112:115], v187, s[64:65] nt
	s_add_u32 s64, s64, 0x2000
	s_addc_u32 s65, s65, 0
	ds_bpermute_b32 v174, v188, v186 offset:124
	s_waitcnt vmcnt(32) lgkmcnt(3)
	v_pk_fma_f32 v[160:161], v[116:117], v[168:169], v[160:161] op_sel_hi:[1,0,1]
	v_pk_fma_f32 v[162:163], v[118:119], v[168:169], v[162:163] op_sel_hi:[1,0,1]
	global_load_dwordx4 v[116:119], v187, s[64:65] nt
	s_add_u32 s64, s64, 0x2000
	s_addc_u32 s65, s65, 0
	s_waitcnt vmcnt(32) lgkmcnt(2)
	v_pk_fma_f32 v[164:165], v[120:121], v[170:171], v[164:165] op_sel_hi:[1,0,1]
	v_pk_fma_f32 v[166:167], v[122:123], v[170:171], v[166:167] op_sel_hi:[1,0,1]
	global_load_dwordx4 v[120:123], v187, s[64:65] nt
	s_add_u32 s64, s64, 0x2000
	s_addc_u32 s65, s65, 0
	s_waitcnt vmcnt(32) lgkmcnt(1)
	v_pk_fma_f32 v[160:161], v[124:125], v[172:173], v[160:161] op_sel_hi:[1,0,1]
	v_pk_fma_f32 v[162:163], v[126:127], v[172:173], v[162:163] op_sel_hi:[1,0,1]
	global_load_dwordx4 v[124:127], v187, s[64:65] nt
	s_add_u32 s64, s64, 0x2000
	s_addc_u32 s65, s65, 0
	s_waitcnt vmcnt(32) lgkmcnt(0)
	v_pk_fma_f32 v[164:165], v[128:129], v[174:175], v[164:165] op_sel_hi:[1,0,1]
	v_pk_fma_f32 v[166:167], v[130:131], v[174:175], v[166:167] op_sel_hi:[1,0,1]
	global_load_dwordx4 v[128:131], v187, s[64:65] nt
	s_add_u32 s64, s64, 0x2000
	s_addc_u32 s65, s65, 0
	s_nop 1
	v_pk_add_f32 v[160:161], v[160:161], v[164:165]
	v_pk_add_f32 v[162:163], v[162:163], v[166:167]
	s_nop 1
	v_mov_b32_e32 v164, v160
	v_mov_b32_e32 v165, v161
	v_mov_b32_e32 v166, v162
	v_mov_b32_e32 v167, v163
	v_permlane32_swap_b32_e32 v160, v164
	v_permlane32_swap_b32_e32 v161, v165
	v_permlane32_swap_b32_e32 v162, v166
	v_permlane32_swap_b32_e32 v163, v167
	v_pk_add_f32 v[160:161], v[160:161], v[164:165]
	v_pk_add_f32 v[162:163], v[162:163], v[166:167]
	s_nop 1
	s_mov_b32 exec_hi, 0
	global_store_dwordx4 v193, v[160:163], s[70:71]
	s_mov_b32 exec_lo, 1
	global_store_dword v189, v183, s[70:71] offset:512
	s_mov_b64 exec, -1
	s_mov_b32 s72, s73
	s_branch .Ldqa_loop
; __device__ __forceinline__ void sb_decode_stream(Frame& F, unsigned* qctr, int base, int limit) {
;     ...
;         for (int i = 0; i < 16; ++i) { const float aj = __shfl(a, 2 * i + half); o4 += aj * A[i]; }
;         const f32x4 q4n = *(const f32x4*)(SSP(S_PROJ) + (size_t)bn * IN_COLS + hn * HD + 4 * l32);
; #pragma unroll
;         for (int i = 0; i < 16; ++i) A[i] = __builtin_nontemporal_load((const f32x4*)(CK + cbn + (size_t)(2 * i) * stepn));
; #pragma unroll
;         for (int i = 0; i < 16; ++i) { const float aj = __shfl(a, 32 + 2 * i + half); o4 += aj * B[i]; }
; #pragma unroll
;         for (int i = 0; i < 16; ++i) B[i] = __builtin_nontemporal_load((const f32x4*)(CK + cbn + (size_t)(32 + 2 * i) * stepn));
;         o4.x += __shfl_xor(o4.x, 32); o4.y += __shfl_xor(o4.y, 32); o4.z += __shfl_xor(o4.z, 32); o4.w += __shfl_xor(o4.w, 32);
.Ldqa_tail:
	s_waitcnt lgkmcnt(0)
	v_mov_b32_e32 v160, 0
	v_mov_b32_e32 v161, 0
	v_mov_b32_e32 v162, 0
	v_mov_b32_e32 v163, 0
	v_mov_b32_e32 v164, 0
	v_mov_b32_e32 v165, 0
	v_mov_b32_e32 v166, 0
	v_mov_b32_e32 v167, 0
	ds_bpermute_b32 v168, v188, v186 offset:0
	ds_bpermute_b32 v170, v188, v186 offset:4
	ds_bpermute_b32 v172, v188, v186 offset:8
	ds_bpermute_b32 v174, v188, v186 offset:12
	s_waitcnt vmcnt(31) lgkmcnt(3)
	v_pk_fma_f32 v[160:161], v[4:5], v[168:169], v[160:161] op_sel_hi:[1,0,1]
	v_pk_fma_f32 v[162:163], v[6:7], v[168:169], v[162:163] op_sel_hi:[1,0,1]
	ds_bpermute_b32 v168, v188, v186 offset:16
	s_waitcnt vmcnt(30) lgkmcnt(3)
	v_pk_fma_f32 v[164:165], v[8:9], v[170:171], v[164:165] op_sel_hi:[1,0,1]
	v_pk_fma_f32 v[166:167], v[10:11], v[170:171], v[166:167] op_sel_hi:[1,0,1]
	ds_bpermute_b32 v170, v188, v186 offset:20
	s_waitcnt vmcnt(29) lgkmcnt(3)
	v_pk_fma_f32 v[160:161], v[12:13], v[172:173], v[160:161] op_sel_hi:[1,0,1]
	v_pk_fma_f32 v[162:163], v[14:15], v[172:173], v[162:163] op_sel_hi:[1,0,1]
	ds_bpermute_b32 v172, v188, v186 offset:24
	s_waitcnt vmcnt(28) lgkmcnt(3)
	v_pk_fma_f32 v[164:165], v[16:17], v[174:175], v[164:165] op_sel_hi:[1,0,1]
	v_pk_fma_f32 v[166:167], v[18:19], v[174:175], v[166:167] op_sel_hi:[1,0,1]
	ds_bpermute_b32 v174, v188, v186 offset:28
	s_waitcnt vmcnt(27) lgkmcnt(3)
	v_pk_fma_f32 v[160:161], v[20:21], v[168:169], v[160:161] op_sel_hi:[1,0,1]
	v_pk_fma_f32 v[162:163], v[22:23], v[168:169], v[162:163] op_sel_hi:[1,0,1]
	ds_bpermute_b32 v168, v188, v186 offset:32
	s_waitcnt vmcnt(26) lgkmcnt(3)
	v_pk_fma_f32 v[164:165], v[24:25], v[170:171], v[164:165] op_sel_hi:[1,0,1]
	v_pk_fma_f32 v[166:167], v[26:27], v[170:171], v[166:167] op_sel_hi:[1,0,1]
	ds_bpermute_b32 v170, v188, v186 offset:36
	s_waitcnt vmcnt(25) lgkmcnt(3)
	v_pk_fma_f32 v[160:161], v[28:29], v[172:173], v[160:161] op_sel_hi:[1,0,1]
	v_pk_fma_f32 v[162:163], v[30:31], v[172:173], v[162:163] op_sel_hi:[1,0,1]
	ds_bpermute_b32 v172, v188, v186 offset:40
	s_waitcnt vmcnt(24) lgkmcnt(3)
	v_pk_fma_f32 v[164:165], v[32:33], v[174:175], v[164:165] op_sel_hi:[1,0,1]
	v_pk_fma_f32 v[166:167], v[34:35], v[174:175], v[166:167] op_sel_hi:[1,0,1]
	ds_bpermute_b32 v174, v188, v186 offset:44
	s_waitcnt vmcnt(23) lgkmcnt(3)
	v_pk_fma_f32 v[160:161], v[36:37], v[168:169], v[160:161] op_sel_hi:[1,0,1]
	v_pk_fma_f32 v[162:163], v[38:39], v[168:169], v[162:163] op_sel_hi:[1,0,1]
	ds_bpermute_b32 v168, v188, v186 offset:48
	s_waitcnt vmcnt(22) lgkmcnt(3)
	v_pk_fma_f32 v[164:165], v[40:41], v[170:171], v[164:165] op_sel_hi:[1,0,1]
	v_pk_fma_f32 v[166:167], v[42:43], v[170:171], v[166:167] op_sel_hi:[1,0,1]
	ds_bpermute_b32 v170, v188, v186 offset:52
	s_waitcnt vmcnt(21) lgkmcnt(3)
	v_pk_fma_f32 v[160:161], v[44:45], v[172:173], v[160:161] op_sel_hi:[1,0,1]
	v_pk_fma_f32 v[162:163], v[46:47], v[172:173], v[162:163] op_sel_hi:[1,0,1]
	ds_bpermute_b32 v172, v188, v186 offset:56
	s_waitcnt vmcnt(20) lgkmcnt(3)
	v_pk_fma_f32 v[164:165], v[48:49], v[174:175], v[164:165] op_sel_hi:[1,0,1]
	v_pk_fma_f32 v[166:167], v[50:51], v[174:175], v[166:167] op_sel_hi:[1,0,1]
	ds_bpermute_b32 v174, v188, v186 offset:60
	s_waitcnt vmcnt(19) lgkmcnt(3)
	v_pk_fma_f32 v[160:161], v[52:53], v[168:169], v[160:161] op_sel_hi:[1,0,1]
	v_pk_fma_f32 v[162:163], v[54:55], v[168:169], v[162:163] op_sel_hi:[1,0,1]
	ds_bpermute_b32 v168, v188, v186 offset:64
	s_waitcnt vmcnt(18) lgkmcnt(3)
	v_pk_fma_f32 v[164:165], v[56:57], v[170:171], v[164:165] op_sel_hi:[1,0,1]
	v_pk_fma_f32 v[166:167], v[58:59], v[170:171], v[166:167] op_sel_hi:[1,0,1]
	ds_bpermute_b32 v170, v188, v186 offset:68
	s_waitcnt vmcnt(17) lgkmcnt(3)
	v_pk_fma_f32 v[160:161], v[60:61], v[172:173], v[160:161] op_sel_hi:[1,0,1]
	v_pk_fma_f32 v[162:163], v[62:63], v[172:173], v[162:163] op_sel_hi:[1,0,1]
	ds_bpermute_b32 v172, v188, v186 offset:72
	s_waitcnt vmcnt(16) lgkmcnt(3)
	v_pk_fma_f32 v[164:165], v[64:65], v[174:175], v[164:165] op_sel_hi:[1,0,1]
	v_pk_fma_f32 v[166:167], v[66:67], v[174:175], v[166:167] op_sel_hi:[1,0,1]
	ds_bpermute_b32 v174, v188, v186 offset:76
	s_waitcnt vmcnt(15) lgkmcnt(3)
; __device__ __forceinline__ void sb_decode_stream(Frame& F, unsigned* qctr, int base, int limit) {
;     ...
;         for (int i = 0; i < 16; ++i) { const float aj = __shfl(a, 2 * i + half); o4 += aj * A[i]; }
;         const f32x4 q4n = *(const f32x4*)(SSP(S_PROJ) + (size_t)bn * IN_COLS + hn * HD + 4 * l32);
; #pragma unroll
;         for (int i = 0; i < 16; ++i) A[i] = __builtin_nontemporal_load((const f32x4*)(CK + cbn + (size_t)(2 * i) * stepn));
; #pragma unroll
;         for (int i = 0; i < 16; ++i) { const float aj = __shfl(a, 32 + 2 * i + half); o4 += aj * B[i]; }
; #pragma unroll
;         for (int i = 0; i < 16; ++i) B[i] = __builtin_nontemporal_load((const f32x4*)(CK + cbn + (size_t)(32 + 2 * i) * stepn));
;         o4.x += __shfl_xor(o4.x, 32); o4.y += __shfl_xor(o4.y, 32); o4.z += __shfl_xor(o4.z, 32); o4.w += __shfl_xor(o4.w, 32);
;         float* P = SSP(S_PART) + ((size_t)bh * DSEG + blk) * DPART;
;         if (half == 0) *(f32x4*)(P + 4 * l32) = o4; if (lane == 0) P[128] = tot;
	v_pk_fma_f32 v[160:161], v[68:69], v[168:169], v[160:161] op_sel_hi:[1,0,1]
	v_pk_fma_f32 v[162:163], v[70:71], v[168:169], v[162:163] op_sel_hi:[1,0,1]
	ds_bpermute_b32 v168, v188, v186 offset:80
	s_waitcnt vmcnt(14) lgkmcnt(3)
	v_pk_fma_f32 v[164:165], v[72:73], v[170:171], v[164:165] op_sel_hi:[1,0,1]
	v_pk_fma_f32 v[166:167], v[74:75], v[170:171], v[166:167] op_sel_hi:[1,0,1]
	ds_bpermute_b32 v170, v188, v186 offset:84
	s_waitcnt vmcnt(13) lgkmcnt(3)
	v_pk_fma_f32 v[160:161], v[76:77], v[172:173], v[160:161] op_sel_hi:[1,0,1]
	v_pk_fma_f32 v[162:163], v[78:79], v[172:173], v[162:163] op_sel_hi:[1,0,1]
	ds_bpermute_b32 v172, v188, v186 offset:88
	s_waitcnt vmcnt(12) lgkmcnt(3)
	v_pk_fma_f32 v[164:165], v[80:81], v[174:175], v[164:165] op_sel_hi:[1,0,1]
	v_pk_fma_f32 v[166:167], v[82:83], v[174:175], v[166:167] op_sel_hi:[1,0,1]
	ds_bpermute_b32 v174, v188, v186 offset:92
	s_waitcnt vmcnt(11) lgkmcnt(3)
	v_pk_fma_f32 v[160:161], v[84:85], v[168:169], v[160:161] op_sel_hi:[1,0,1]
	v_pk_fma_f32 v[162:163], v[86:87], v[168:169], v[162:163] op_sel_hi:[1,0,1]
	ds_bpermute_b32 v168, v188, v186 offset:96
	s_waitcnt vmcnt(10) lgkmcnt(3)
	v_pk_fma_f32 v[164:165], v[88:89], v[170:171], v[164:165] op_sel_hi:[1,0,1]
	v_pk_fma_f32 v[166:167], v[90:91], v[170:171], v[166:167] op_sel_hi:[1,0,1]
	ds_bpermute_b32 v170, v188, v186 offset:100
	s_waitcnt vmcnt(9) lgkmcnt(3)
	v_pk_fma_f32 v[160:161], v[92:93], v[172:173], v[160:161] op_sel_hi:[1,0,1]
	v_pk_fma_f32 v[162:163], v[94:95], v[172:173], v[162:163] op_sel_hi:[1,0,1]
	ds_bpermute_b32 v172, v188, v186 offset:104
	s_waitcnt vmcnt(8) lgkmcnt(3)
	v_pk_fma_f32 v[164:165], v[96:97], v[174:175], v[164:165] op_sel_hi:[1,0,1]
	v_pk_fma_f32 v[166:167], v[98:99], v[174:175], v[166:167] op_sel_hi:[1,0,1]
	ds_bpermute_b32 v174, v188, v186 offset:108
	s_waitcnt vmcnt(7) lgkmcnt(3)
	v_pk_fma_f32 v[160:161], v[100:101], v[168:169], v[160:161] op_sel_hi:[1,0,1]
	v_pk_fma_f32 v[162:163], v[102:103], v[168:169], v[162:163] op_sel_hi:[1,0,1]
	ds_bpermute_b32 v168, v188, v186 offset:112
	s_waitcnt vmcnt(6) lgkmcnt(3)
	v_pk_fma_f32 v[164:165], v[104:105], v[170:171], v[164:165] op_sel_hi:[1,0,1]
	v_pk_fma_f32 v[166:167], v[106:107], v[170:171], v[166:167] op_sel_hi:[1,0,1]
	ds_bpermute_b32 v170, v188, v186 offset:116
	s_waitcnt vmcnt(5) lgkmcnt(3)
	v_pk_fma_f32 v[160:161], v[108:109], v[172:173], v[160:161] op_sel_hi:[1,0,1]
	v_pk_fma_f32 v[162:163], v[110:111], v[172:173], v[162:163] op_sel_hi:[1,0,1]
	ds_bpermute_b32 v172, v188, v186 offset:120
	s_waitcnt vmcnt(4) lgkmcnt(3)
	v_pk_fma_f32 v[164:165], v[112:113], v[174:175], v[164:165] op_sel_hi:[1,0,1]
	v_pk_fma_f32 v[166:167], v[114:115], v[174:175], v[166:167] op_sel_hi:[1,0,1]
	ds_bpermute_b32 v174, v188, v186 offset:124
	s_waitcnt vmcnt(3) lgkmcnt(3)
	v_pk_fma_f32 v[160:161], v[116:117], v[168:169], v[160:161] op_sel_hi:[1,0,1]
	v_pk_fma_f32 v[162:163], v[118:119], v[168:169], v[162:163] op_sel_hi:[1,0,1]
	s_waitcnt vmcnt(2) lgkmcnt(2)
	v_pk_fma_f32 v[164:165], v[120:121], v[170:171], v[164:165] op_sel_hi:[1,0,1]
	v_pk_fma_f32 v[166:167], v[122:123], v[170:171], v[166:167] op_sel_hi:[1,0,1]
	s_waitcnt vmcnt(1) lgkmcnt(1)
	v_pk_fma_f32 v[160:161], v[124:125], v[172:173], v[160:161] op_sel_hi:[1,0,1]
	v_pk_fma_f32 v[162:163], v[126:127], v[172:173], v[162:163] op_sel_hi:[1,0,1]
	s_waitcnt vmcnt(0) lgkmcnt(0)
	v_pk_fma_f32 v[164:165], v[128:129], v[174:175], v[164:165] op_sel_hi:[1,0,1]
	v_pk_fma_f32 v[166:167], v[130:131], v[174:175], v[166:167] op_sel_hi:[1,0,1]
	s_nop 1
	v_pk_add_f32 v[160:161], v[160:161], v[164:165]
	v_pk_add_f32 v[162:163], v[162:163], v[166:167]
	s_nop 1
	v_mov_b32_e32 v164, v160
	v_mov_b32_e32 v165, v161
	v_mov_b32_e32 v166, v162
	v_mov_b32_e32 v167, v163
	v_permlane32_swap_b32_e32 v160, v164
	v_permlane32_swap_b32_e32 v161, v165
	v_permlane32_swap_b32_e32 v162, v166
	v_permlane32_swap_b32_e32 v163, v167
	v_pk_add_f32 v[160:161], v[160:161], v[164:165]
	v_pk_add_f32 v[162:163], v[162:163], v[166:167]
	s_nop 1
	s_mov_b32 exec_hi, 0
	global_store_dwordx4 v193, v[160:163], s[70:71]
	s_mov_b32 exec_lo, 1
	global_store_dword v189, v183, s[70:71] offset:512
	s_mov_b64 exec, -1

; __device__ __forceinline__ void sb_decode_stream(Frame& F, unsigned* qctr, int base, int limit) {
;     ...
;         DEC_SCORES(A, 0);
; #pragma unroll
;         for (int i = 0; i < 16; ++i) A[i] = __builtin_nontemporal_load((const f32x4*)(CV + cb + (size_t)(2 * i) * (NH * HD)));
;         DEC_SCORES(B, 1);
;     ...
; #pragma unroll
;         for (int i = 0; i < 16; ++i) B[i] = __builtin_nontemporal_load((const f32x4*)(CV + cb + (size_t)(32 + 2 * i) * (NH * HD)));
;         const float z = __builtin_bit_cast(float, zi);
;         const float e = __builtin_amdgcn_exp2f(-(z * k1 + k2));
;         const float be = __builtin_amdgcn_rcpf(1.0f + e), m = 1.0f - be;
;         float s = m;
; #pragma unroll
;         for (int o = 1; o < 64; o <<= 1) { const float t = __shfl_down(s, o); if (lane + o < 64) s *= t; }
;         const float tot = __shfl(s, 0);
;         const float sx = __shfl_down(s, 1);
;         const float a = be * (lane < 63 ? sx : 1.0f);
;         int itn = (int)(__builtin_amdgcn_readfirstlane(vn) >> 6); const bool more = itn < limit; itn = more ? itn + base : it;
;         const int bn = itn >> 11, hn = itn & 7, p0n = ((itn >> 3) & 255) * 64;
;         const int pagen = PT[bn * NPAGES + (p0n >> 7)];
;         const size_t cbn = (((size_t)pagen * PAGE + (p0n & 127)) * NH + hn) * HD + lo;
;         const size_t stepn = more ? (size_t)(NH * HD) : 0;
;         f32x4 o4 = {0.f, 0.f, 0.f, 0.f};
; #pragma unroll
;         for (int i = 0; i < 16; ++i) { const float aj = __shfl(a, 2 * i + half); o4 += aj * A[i]; }
;         const f32x4 q4n = *(const f32x4*)(SSP(S_PROJ) + (size_t)bn * IN_COLS + hn * HD + 4 * l32);
; #pragma unroll
;         for (int i = 0; i < 16; ++i) A[i] = __builtin_nontemporal_load((const f32x4*)(CK + cbn + (size_t)(2 * i) * stepn));
.Ldqc_sh2:
	s_barrier
	ds_read_b32 v201, v200
	s_xor_b32 s37, s37, 4
	s_waitcnt lgkmcnt(0)
	v_readfirstlane_b32 s2, v201
	s_nop 0
	s_lshr_b32 s73, s2, 6
	s_cmp_lt_u32 s73, 0x2800
	s_cselect_b32 s31, 1, 0
	s_add_u32 s73, s73, s94
	s_min_u32 s73, s73, 0x27ff
	s_add_u32 s73, s73, 0x1800
	s_cmp_eq_u32 s31, 1
	s_cselect_b32 s73, s73, s72
	s_lshr_b32 s6, s73, 11
	s_and_b32 s7, s73, 7
	s_bfe_u32 s8, s73, 0x80003
	s_lshl_b32 s9, s6, 7
	s_lshr_b32 s10, s8, 1
	s_or_b32 s9, s9, s10
	s_lshl_b32 s9, s9, 2
	s_lshl_b32 s10, s7, 2
	s_load_dword s29, s[54:55], s9
	s_load_dword s30, s[56:57], s10
	v_add_f32_dpp v132, v132, v132 row_ror:8 row_mask:0xf bank_mask:0x3
	v_add_f32_dpp v133, v133, v133 row_ror:8 row_mask:0xf bank_mask:0x3
	v_add_f32_dpp v134, v134, v134 row_ror:8 row_mask:0xf bank_mask:0x3
	v_add_f32_dpp v135, v135, v135 row_ror:8 row_mask:0xf bank_mask:0x3
	v_add_f32_dpp v136, v136, v136 row_ror:8 row_mask:0xf bank_mask:0x3
	v_add_f32_dpp v137, v137, v137 row_ror:8 row_mask:0xf bank_mask:0x3
	v_add_f32_dpp v138, v138, v138 row_ror:8 row_mask:0xf bank_mask:0x3
	v_add_f32_dpp v139, v139, v139 row_ror:8 row_mask:0xf bank_mask:0x3
	v_add_f32_dpp v132, v140, v140 row_ror:8 row_mask:0xf bank_mask:0xc
	v_add_f32_dpp v133, v141, v141 row_ror:8 row_mask:0xf bank_mask:0xc
	v_add_f32_dpp v134, v142, v142 row_ror:8 row_mask:0xf bank_mask:0xc
	v_add_f32_dpp v135, v143, v143 row_ror:8 row_mask:0xf bank_mask:0xc
	v_add_f32_dpp v136, v144, v144 row_ror:8 row_mask:0xf bank_mask:0xc
	v_add_f32_dpp v137, v145, v145 row_ror:8 row_mask:0xf bank_mask:0xc
	v_add_f32_dpp v138, v146, v146 row_ror:8 row_mask:0xf bank_mask:0xc
	v_add_f32_dpp v139, v147, v147 row_ror:8 row_mask:0xf bank_mask:0xc
	v_add_f32_dpp v132, v132, v132 row_ror:12 row_mask:0xf bank_mask:0x5
	v_add_f32_dpp v133, v133, v133 row_ror:12 row_mask:0xf bank_mask:0x5
	v_add_f32_dpp v134, v134, v134 row_ror:12 row_mask:0xf bank_mask:0x5
	v_add_f32_dpp v135, v135, v135 row_ror:12 row_mask:0xf bank_mask:0x5
	v_add_f32_dpp v132, v136, v136 row_ror:4 row_mask:0xf bank_mask:0xa
	v_add_f32_dpp v133, v137, v137 row_ror:4 row_mask:0xf bank_mask:0xa
	v_add_f32_dpp v134, v138, v138 row_ror:4 row_mask:0xf bank_mask:0xa
	v_add_f32_dpp v135, v139, v139 row_ror:4 row_mask:0xf bank_mask:0xa
	v_add_f32_dpp v140, v132, v132 quad_perm:[2,3,0,1] row_mask:0xf bank_mask:0xf
	v_add_f32_dpp v142, v134, v134 quad_perm:[2,3,0,1] row_mask:0xf bank_mask:0xf
	v_add_f32_dpp v141, v133, v133 quad_perm:[2,3,0,1] row_mask:0xf bank_mask:0xf
	v_add_f32_dpp v143, v135, v135 quad_perm:[2,3,0,1] row_mask:0xf bank_mask:0xf
	v_cndmask_b32_e64 v132, v140, v142, s[76:77]
	v_cndmask_b32_e64 v133, v141, v143, s[76:77]
	s_nop 0
	v_add_f32_dpp v196, v132, v132 quad_perm:[1,0,3,2] row_mask:0xf bank_mask:0xf
	v_add_f32_dpp v197, v133, v133 quad_perm:[1,0,3,2] row_mask:0xf bank_mask:0xf
	v_cndmask_b32_e64 v177, v196, v197, s[78:79]
	s_nop 1
	v_permlane16_swap_b32_e32 v176, v177
	v_add_f32_e32 v178, v176, v177
	v_mul_f32_e32 v178, 0x3e0293ee, v178
	v_add_f32_e32 v178, v178, v192
	v_exp_f32_e64 v198, -v178
	s_nop 0
	v_add_f32_e32 v198, 1.0, v198
	v_rcp_f32_e32 v179, v198
	s_nop 0
	v_sub_f32_e32 v180, 1.0, v179
	v_mov_b32_e32 v181, v180
	s_nop 1
	v_permlane32_swap_b32_e32 v180, v181
	v_mul_f32_e32 v183, v180, v181
	s_nop 1
	v_mul_f32_dpp v183, v183, v183 row_shl:1 row_mask:0xf bank_mask:0xf
	s_nop 1
	v_mul_f32_dpp v183, v183, v183 row_shl:2 row_mask:0xf bank_mask:0xf
	s_nop 1
	v_mul_f32_dpp v183, v183, v183 row_shl:4 row_mask:0xf bank_mask:0xf
	s_nop 1
	v_mul_f32_dpp v183, v183, v183 row_shl:8 row_mask:0xf bank_mask:0xf
	s_nop 0
	v_readlane_b32 s33, v183, 16
	v_mov_b32_e32 v184, 1.0
	s_nop 0
	v_mov_b32_e32 v185, s33
	s_nop 1
	v_mul_f32_dpp v183, v183, v185 quad_perm:[0,1,2,3] row_mask:0x5 bank_mask:0xf
	v_mov_b32_dpp v184, v185 quad_perm:[0,1,2,3] row_mask:0x5 bank_mask:0xf
	s_nop 1
	v_mov_b32_dpp v184, v183 row_shl:1 row_mask:0xf bank_mask:0xf
	v_mul_f32_e32 v186, v179, v184
	s_nop 1
	v_mul_f32_dpp v186, v186, v181 quad_perm:[0,1,2,3] row_mask:0x3 bank_mask:0xf
	s_cmp_eq_u32 s31, 0
	s_cbranch_scc1 .Ldqc_tail
	s_waitcnt lgkmcnt(0)
	s_mov_b32 s12, s29
	s_mov_b32 s13, 0
	s_lshl_b64 s[12:13], s[12:13], 19
	s_and_b32 s14, s8, 1
	s_lshl_b32 s14, s14, 18
	s_lshl_b32 s15, s7, 9
	s_or_b32 s14, s14, s15
	s_or_b32 s80, s12, s14
	s_mov_b32 s81, s13
	s_add_u32 s64, s50, s80
	s_addc_u32 s65, s51, s81
	s_mul_i32 s16, s6, 0x7040
	s_add_u32 s16, s16, s15
	s_add_u32 s16, s60, s16
	s_addc_u32 s17, s61, 0
	global_load_dwordx4 v[156:159], v193, s[16:17]
	v_mov_b32_e32 v160, 0
	v_mov_b32_e32 v161, 0
	v_mov_b32_e32 v162, 0
	v_mov_b32_e32 v163, 0
	v_mov_b32_e32 v164, 0
	v_mov_b32_e32 v165, 0
	v_mov_b32_e32 v166, 0
	v_mov_b32_e32 v167, 0
	ds_bpermute_b32 v168, v188, v186 offset:0
	ds_bpermute_b32 v170, v188, v186 offset:4
	ds_bpermute_b32 v172, v188, v186 offset:8
	ds_bpermute_b32 v174, v188, v186 offset:12
	s_waitcnt vmcnt(32) lgkmcnt(3)
	v_pk_fma_f32 v[160:161], v[4:5], v[168:169], v[160:161] op_sel_hi:[1,0,1]
	v_pk_fma_f32 v[162:163], v[6:7], v[168:169], v[162:163] op_sel_hi:[1,0,1]
	global_load_dwordx4 v[4:7], v187, s[64:65] nt
	s_add_u32 s64, s64, 0x2000
	s_addc_u32 s65, s65, 0
	ds_bpermute_b32 v168, v188, v186 offset:16
	s_waitcnt vmcnt(32) lgkmcnt(3)
	v_pk_fma_f32 v[164:165], v[8:9], v[170:171], v[164:165] op_sel_hi:[1,0,1]
	v_pk_fma_f32 v[166:167], v[10:11], v[170:171], v[166:167] op_sel_hi:[1,0,1]
	global_load_dwordx4 v[8:11], v187, s[64:65] nt
	s_add_u32 s64, s64, 0x2000
	s_addc_u32 s65, s65, 0
	ds_bpermute_b32 v170, v188, v186 offset:20
	s_waitcnt vmcnt(32) lgkmcnt(3)
; __device__ __forceinline__ void sb_decode_stream(Frame& F, unsigned* qctr, int base, int limit) {
;     ...
;         for (int i = 0; i < 16; ++i) { const float aj = __shfl(a, 2 * i + half); o4 += aj * A[i]; }
;         const f32x4 q4n = *(const f32x4*)(SSP(S_PROJ) + (size_t)bn * IN_COLS + hn * HD + 4 * l32);
; #pragma unroll
;         for (int i = 0; i < 16; ++i) A[i] = __builtin_nontemporal_load((const f32x4*)(CK + cbn + (size_t)(2 * i) * stepn));
	v_pk_fma_f32 v[160:161], v[12:13], v[172:173], v[160:161] op_sel_hi:[1,0,1]
	v_pk_fma_f32 v[162:163], v[14:15], v[172:173], v[162:163] op_sel_hi:[1,0,1]
	global_load_dwordx4 v[12:15], v187, s[64:65] nt
	s_add_u32 s64, s64, 0x2000
	s_addc_u32 s65, s65, 0
	ds_bpermute_b32 v172, v188, v186 offset:24
	s_waitcnt vmcnt(32) lgkmcnt(3)
	v_pk_fma_f32 v[164:165], v[16:17], v[174:175], v[164:165] op_sel_hi:[1,0,1]
	v_pk_fma_f32 v[166:167], v[18:19], v[174:175], v[166:167] op_sel_hi:[1,0,1]
	global_load_dwordx4 v[16:19], v187, s[64:65] nt
	s_add_u32 s64, s64, 0x2000
	s_addc_u32 s65, s65, 0
	ds_bpermute_b32 v174, v188, v186 offset:28
	s_waitcnt vmcnt(32) lgkmcnt(3)
	v_pk_fma_f32 v[160:161], v[20:21], v[168:169], v[160:161] op_sel_hi:[1,0,1]
	v_pk_fma_f32 v[162:163], v[22:23], v[168:169], v[162:163] op_sel_hi:[1,0,1]
	global_load_dwordx4 v[20:23], v187, s[64:65] nt
	s_add_u32 s64, s64, 0x2000
	s_addc_u32 s65, s65, 0
	ds_bpermute_b32 v168, v188, v186 offset:32
	s_waitcnt vmcnt(32) lgkmcnt(3)
	v_pk_fma_f32 v[164:165], v[24:25], v[170:171], v[164:165] op_sel_hi:[1,0,1]
	v_pk_fma_f32 v[166:167], v[26:27], v[170:171], v[166:167] op_sel_hi:[1,0,1]
	global_load_dwordx4 v[24:27], v187, s[64:65] nt
	s_add_u32 s64, s64, 0x2000
	s_addc_u32 s65, s65, 0
	ds_bpermute_b32 v170, v188, v186 offset:36
	s_waitcnt vmcnt(32) lgkmcnt(3)
	v_pk_fma_f32 v[160:161], v[28:29], v[172:173], v[160:161] op_sel_hi:[1,0,1]
	v_pk_fma_f32 v[162:163], v[30:31], v[172:173], v[162:163] op_sel_hi:[1,0,1]
	global_load_dwordx4 v[28:31], v187, s[64:65] nt
	s_add_u32 s64, s64, 0x2000
	s_addc_u32 s65, s65, 0
	ds_bpermute_b32 v172, v188, v186 offset:40
	s_waitcnt vmcnt(32) lgkmcnt(3)
	v_pk_fma_f32 v[164:165], v[32:33], v[174:175], v[164:165] op_sel_hi:[1,0,1]
	v_pk_fma_f32 v[166:167], v[34:35], v[174:175], v[166:167] op_sel_hi:[1,0,1]
	global_load_dwordx4 v[32:35], v187, s[64:65] nt
	s_add_u32 s64, s64, 0x2000
	s_addc_u32 s65, s65, 0
	ds_bpermute_b32 v174, v188, v186 offset:44
	s_waitcnt vmcnt(32) lgkmcnt(3)
	v_pk_fma_f32 v[160:161], v[36:37], v[168:169], v[160:161] op_sel_hi:[1,0,1]
	v_pk_fma_f32 v[162:163], v[38:39], v[168:169], v[162:163] op_sel_hi:[1,0,1]
	global_load_dwordx4 v[36:39], v187, s[64:65] nt
	s_add_u32 s64, s64, 0x2000
	s_addc_u32 s65, s65, 0
	ds_bpermute_b32 v168, v188, v186 offset:48
	s_waitcnt vmcnt(32) lgkmcnt(3)
	v_pk_fma_f32 v[164:165], v[40:41], v[170:171], v[164:165] op_sel_hi:[1,0,1]
	v_pk_fma_f32 v[166:167], v[42:43], v[170:171], v[166:167] op_sel_hi:[1,0,1]
	global_load_dwordx4 v[40:43], v187, s[64:65] nt
	s_add_u32 s64, s64, 0x2000
	s_addc_u32 s65, s65, 0
	ds_bpermute_b32 v170, v188, v186 offset:52
	s_waitcnt vmcnt(32) lgkmcnt(3)
	v_pk_fma_f32 v[160:161], v[44:45], v[172:173], v[160:161] op_sel_hi:[1,0,1]
	v_pk_fma_f32 v[162:163], v[46:47], v[172:173], v[162:163] op_sel_hi:[1,0,1]
	global_load_dwordx4 v[44:47], v187, s[64:65] nt
	s_add_u32 s64, s64, 0x2000
	s_addc_u32 s65, s65, 0
	ds_bpermute_b32 v172, v188, v186 offset:56
	s_waitcnt vmcnt(32) lgkmcnt(3)
	v_pk_fma_f32 v[164:165], v[48:49], v[174:175], v[164:165] op_sel_hi:[1,0,1]
	v_pk_fma_f32 v[166:167], v[50:51], v[174:175], v[166:167] op_sel_hi:[1,0,1]
	global_load_dwordx4 v[48:51], v187, s[64:65] nt
	s_add_u32 s64, s64, 0x2000
	s_addc_u32 s65, s65, 0
	ds_bpermute_b32 v174, v188, v186 offset:60
	s_waitcnt vmcnt(32) lgkmcnt(3)
	v_pk_fma_f32 v[160:161], v[52:53], v[168:169], v[160:161] op_sel_hi:[1,0,1]
	v_pk_fma_f32 v[162:163], v[54:55], v[168:169], v[162:163] op_sel_hi:[1,0,1]
	global_load_dwordx4 v[52:55], v187, s[64:65] nt
	s_add_u32 s64, s64, 0x2000
	s_addc_u32 s65, s65, 0
	ds_bpermute_b32 v168, v188, v186 offset:64
	s_waitcnt vmcnt(32) lgkmcnt(3)
	v_pk_fma_f32 v[164:165], v[56:57], v[170:171], v[164:165] op_sel_hi:[1,0,1]
	v_pk_fma_f32 v[166:167], v[58:59], v[170:171], v[166:167] op_sel_hi:[1,0,1]
	global_load_dwordx4 v[56:59], v187, s[64:65] nt
	s_add_u32 s64, s64, 0x2000
	s_addc_u32 s65, s65, 0
	ds_bpermute_b32 v170, v188, v186 offset:68
	s_waitcnt vmcnt(32) lgkmcnt(3)
	v_pk_fma_f32 v[160:161], v[60:61], v[172:173], v[160:161] op_sel_hi:[1,0,1]
	v_pk_fma_f32 v[162:163], v[62:63], v[172:173], v[162:163] op_sel_hi:[1,0,1]
	global_load_dwordx4 v[60:63], v187, s[64:65] nt
	s_add_u32 s64, s64, 0x2000
	s_addc_u32 s65, s65, 0
	ds_bpermute_b32 v172, v188, v186 offset:72
	s_waitcnt vmcnt(32) lgkmcnt(3)
	v_pk_fma_f32 v[164:165], v[64:65], v[174:175], v[164:165] op_sel_hi:[1,0,1]
	v_pk_fma_f32 v[166:167], v[66:67], v[174:175], v[166:167] op_sel_hi:[1,0,1]
	global_load_dwordx4 v[64:67], v187, s[64:65] nt
	s_add_u32 s64, s64, 0x2000
	s_addc_u32 s65, s65, 0
	ds_bpermute_b32 v174, v188, v186 offset:76
	s_waitcnt vmcnt(32) lgkmcnt(3)
	v_pk_fma_f32 v[160:161], v[68:69], v[168:169], v[160:161] op_sel_hi:[1,0,1]
	v_pk_fma_f32 v[162:163], v[70:71], v[168:169], v[162:163] op_sel_hi:[1,0,1]
	global_load_dwordx4 v[68:71], v187, s[64:65] nt
	s_add_u32 s64, s64, 0x2000
	s_addc_u32 s65, s65, 0
	ds_bpermute_b32 v168, v188, v186 offset:80
	s_waitcnt vmcnt(32) lgkmcnt(3)
	v_pk_fma_f32 v[164:165], v[72:73], v[170:171], v[164:165] op_sel_hi:[1,0,1]
	v_pk_fma_f32 v[166:167], v[74:75], v[170:171], v[166:167] op_sel_hi:[1,0,1]
	global_load_dwordx4 v[72:75], v187, s[64:65] nt
	s_add_u32 s64, s64, 0x2000
	s_addc_u32 s65, s65, 0
	ds_bpermute_b32 v170, v188, v186 offset:84
	s_waitcnt vmcnt(32) lgkmcnt(3)
; __device__ __forceinline__ void sb_decode_stream(Frame& F, unsigned* qctr, int base, int limit) {
;     ...
;         for (int i = 0; i < 16; ++i) { const float aj = __shfl(a, 2 * i + half); o4 += aj * A[i]; }
;         const f32x4 q4n = *(const f32x4*)(SSP(S_PROJ) + (size_t)bn * IN_COLS + hn * HD + 4 * l32);
; #pragma unroll
;         for (int i = 0; i < 16; ++i) A[i] = __builtin_nontemporal_load((const f32x4*)(CK + cbn + (size_t)(2 * i) * stepn));
; #pragma unroll
;         for (int i = 0; i < 16; ++i) { const float aj = __shfl(a, 32 + 2 * i + half); o4 += aj * B[i]; }
; #pragma unroll
;         for (int i = 0; i < 16; ++i) B[i] = __builtin_nontemporal_load((const f32x4*)(CK + cbn + (size_t)(32 + 2 * i) * stepn));
;         o4.x += __shfl_xor(o4.x, 32); o4.y += __shfl_xor(o4.y, 32); o4.z += __shfl_xor(o4.z, 32); o4.w += __shfl_xor(o4.w, 32);
;         float* P = SSP(S_PART) + ((size_t)bh * DSEG + blk) * DPART;
;         if (half == 0) *(f32x4*)(P + 4 * l32) = o4; if (lane == 0) P[128] = tot;
;         if (!more) break;
;         it = itn; cb = cbn; q4 = q4n;
;     }
	v_pk_fma_f32 v[160:161], v[76:77], v[172:173], v[160:161] op_sel_hi:[1,0,1]
	v_pk_fma_f32 v[162:163], v[78:79], v[172:173], v[162:163] op_sel_hi:[1,0,1]
	global_load_dwordx4 v[76:79], v187, s[64:65] nt
	s_add_u32 s64, s64, 0x2000
	s_addc_u32 s65, s65, 0
	ds_bpermute_b32 v172, v188, v186 offset:88
	s_waitcnt vmcnt(32) lgkmcnt(3)
	v_pk_fma_f32 v[164:165], v[80:81], v[174:175], v[164:165] op_sel_hi:[1,0,1]
	v_pk_fma_f32 v[166:167], v[82:83], v[174:175], v[166:167] op_sel_hi:[1,0,1]
	global_load_dwordx4 v[80:83], v187, s[64:65] nt
	s_add_u32 s64, s64, 0x2000
	s_addc_u32 s65, s65, 0
	ds_bpermute_b32 v174, v188, v186 offset:92
	s_waitcnt vmcnt(32) lgkmcnt(3)
	v_pk_fma_f32 v[160:161], v[84:85], v[168:169], v[160:161] op_sel_hi:[1,0,1]
	v_pk_fma_f32 v[162:163], v[86:87], v[168:169], v[162:163] op_sel_hi:[1,0,1]
	global_load_dwordx4 v[84:87], v187, s[64:65] nt
	s_add_u32 s64, s64, 0x2000
	s_addc_u32 s65, s65, 0
	ds_bpermute_b32 v168, v188, v186 offset:96
	s_waitcnt vmcnt(32) lgkmcnt(3)
	v_pk_fma_f32 v[164:165], v[88:89], v[170:171], v[164:165] op_sel_hi:[1,0,1]
	v_pk_fma_f32 v[166:167], v[90:91], v[170:171], v[166:167] op_sel_hi:[1,0,1]
	global_load_dwordx4 v[88:91], v187, s[64:65] nt
	s_add_u32 s64, s64, 0x2000
	s_addc_u32 s65, s65, 0
	ds_bpermute_b32 v170, v188, v186 offset:100
	s_waitcnt vmcnt(32) lgkmcnt(3)
	v_pk_fma_f32 v[160:161], v[92:93], v[172:173], v[160:161] op_sel_hi:[1,0,1]
	v_pk_fma_f32 v[162:163], v[94:95], v[172:173], v[162:163] op_sel_hi:[1,0,1]
	global_load_dwordx4 v[92:95], v187, s[64:65] nt
	s_add_u32 s64, s64, 0x2000
	s_addc_u32 s65, s65, 0
	ds_bpermute_b32 v172, v188, v186 offset:104
	s_waitcnt vmcnt(32) lgkmcnt(3)
	v_pk_fma_f32 v[164:165], v[96:97], v[174:175], v[164:165] op_sel_hi:[1,0,1]
	v_pk_fma_f32 v[166:167], v[98:99], v[174:175], v[166:167] op_sel_hi:[1,0,1]
	global_load_dwordx4 v[96:99], v187, s[64:65] nt
	s_add_u32 s64, s64, 0x2000
	s_addc_u32 s65, s65, 0
	ds_bpermute_b32 v174, v188, v186 offset:108
	s_waitcnt vmcnt(32) lgkmcnt(3)
	v_pk_fma_f32 v[160:161], v[100:101], v[168:169], v[160:161] op_sel_hi:[1,0,1]
	v_pk_fma_f32 v[162:163], v[102:103], v[168:169], v[162:163] op_sel_hi:[1,0,1]
	global_load_dwordx4 v[100:103], v187, s[64:65] nt
	s_add_u32 s64, s64, 0x2000
	s_addc_u32 s65, s65, 0
	ds_bpermute_b32 v168, v188, v186 offset:112
	s_waitcnt vmcnt(32) lgkmcnt(3)
	v_pk_fma_f32 v[164:165], v[104:105], v[170:171], v[164:165] op_sel_hi:[1,0,1]
	v_pk_fma_f32 v[166:167], v[106:107], v[170:171], v[166:167] op_sel_hi:[1,0,1]
	global_load_dwordx4 v[104:107], v187, s[64:65] nt
	s_add_u32 s64, s64, 0x2000
	s_addc_u32 s65, s65, 0
	ds_bpermute_b32 v170, v188, v186 offset:116
	s_waitcnt vmcnt(32) lgkmcnt(3)
	v_pk_fma_f32 v[160:161], v[108:109], v[172:173], v[160:161] op_sel_hi:[1,0,1]
	v_pk_fma_f32 v[162:163], v[110:111], v[172:173], v[162:163] op_sel_hi:[1,0,1]
	global_load_dwordx4 v[108:111], v187, s[64:65] nt
	s_add_u32 s64, s64, 0x2000
	s_addc_u32 s65, s65, 0
	ds_bpermute_b32 v172, v188, v186 offset:120
	s_waitcnt vmcnt(32) lgkmcnt(3)
	v_pk_fma_f32 v[164:165], v[112:113], v[174:175], v[164:165] op_sel_hi:[1,0,1]
	v_pk_fma_f32 v[166:167], v[114:115], v[174:175], v[166:167] op_sel_hi:[1,0,1]
	global_load_dwordx4 v[112:115], v187, s[64:65] nt
	s_add_u32 s64, s64, 0x2000
	s_addc_u32 s65, s65, 0
	ds_bpermute_b32 v174, v188, v186 offset:124
	s_waitcnt vmcnt(32) lgkmcnt(3)
	v_pk_fma_f32 v[160:161], v[116:117], v[168:169], v[160:161] op_sel_hi:[1,0,1]
	v_pk_fma_f32 v[162:163], v[118:119], v[168:169], v[162:163] op_sel_hi:[1,0,1]
	global_load_dwordx4 v[116:119], v187, s[64:65] nt
	s_add_u32 s64, s64, 0x2000
	s_addc_u32 s65, s65, 0
	s_waitcnt vmcnt(32) lgkmcnt(2)
	v_pk_fma_f32 v[164:165], v[120:121], v[170:171], v[164:165] op_sel_hi:[1,0,1]
	v_pk_fma_f32 v[166:167], v[122:123], v[170:171], v[166:167] op_sel_hi:[1,0,1]
	global_load_dwordx4 v[120:123], v187, s[64:65] nt
	s_add_u32 s64, s64, 0x2000
	s_addc_u32 s65, s65, 0
	s_waitcnt vmcnt(32) lgkmcnt(1)
	v_pk_fma_f32 v[160:161], v[124:125], v[172:173], v[160:161] op_sel_hi:[1,0,1]
	v_pk_fma_f32 v[162:163], v[126:127], v[172:173], v[162:163] op_sel_hi:[1,0,1]
	global_load_dwordx4 v[124:127], v187, s[64:65] nt
	s_add_u32 s64, s64, 0x2000
	s_addc_u32 s65, s65, 0
	s_waitcnt vmcnt(32) lgkmcnt(0)
	v_pk_fma_f32 v[164:165], v[128:129], v[174:175], v[164:165] op_sel_hi:[1,0,1]
	v_pk_fma_f32 v[166:167], v[130:131], v[174:175], v[166:167] op_sel_hi:[1,0,1]
	global_load_dwordx4 v[128:131], v187, s[64:65] nt
	s_add_u32 s64, s64, 0x2000
	s_addc_u32 s65, s65, 0
	s_nop 1
	v_pk_add_f32 v[160:161], v[160:161], v[164:165]
	v_pk_add_f32 v[162:163], v[162:163], v[166:167]
	s_nop 1
	v_mov_b32_e32 v164, v160
	v_mov_b32_e32 v165, v161
	v_mov_b32_e32 v166, v162
	v_mov_b32_e32 v167, v163
	v_permlane32_swap_b32_e32 v160, v164
	v_permlane32_swap_b32_e32 v161, v165
	v_permlane32_swap_b32_e32 v162, v166
	v_permlane32_swap_b32_e32 v163, v167
	v_pk_add_f32 v[160:161], v[160:161], v[164:165]
	v_pk_add_f32 v[162:163], v[162:163], v[166:167]
	s_nop 1
	s_mov_b32 exec_hi, 0
	global_store_dwordx4 v193, v[160:163], s[70:71]
	s_mov_b32 exec_lo, 1
	global_store_dword v189, v183, s[70:71] offset:512
	s_mov_b64 exec, -1
	s_mov_b32 s72, s73
	s_branch .Ldqc_loop
